# layer-1 W_in/W_out/kv-cache bf16 conversion done by workgroups idle in the last round of layer-0 up-projection GEMM
# baseline (speedup 1.0000x reference)
.LBB0_400:
	s_andn2_b64 vcc, exec, s[0:1]
	s_cbranch_vccnz .LBB0_558
	s_cmp_lg_u32 s63, 0
	s_cselect_b64 s[2:3], -1, 0
	s_and_b64 vcc, exec, s[2:3]
	s_cbranch_vccnz .LBB0_437
	s_mov_b64 s[8:9], s[36:37]
	s_waitcnt vmcnt(0)
	v_mov_b32_e32 v1, v224
	v_readlane_b32 s0, v253, 0
	v_ashrrev_i32_e32 v0, 6, v1
	v_readlane_b32 s1, v254, 21
	s_and_b32 s6, s1, 0xffff
	v_lshl_add_u32 v4, s0, 3, v0
	s_mul_i32 s1, s6, 0x910
	v_add_u32_e32 v4, s1, v4
	s_movk_i32 s1, 0x1990
	s_mov_b32 s0, s54
	v_cmp_gt_i32_e32 vcc, s1, v4
	s_and_saveexec_b64 s[10:11], vcc
	s_cbranch_execz .LBB0_421
	s_load_dwordx2 s[4:5], s[8:9], 0x48
	s_load_dwordx4 s[20:23], s[8:9], 0x78
	s_lshl_b32 s7, s0, 3
	s_mul_i32 s1, s6, 0xe08000
	v_and_b32_e32 v3, 7, v1
	s_waitcnt lgkmcnt(0)
	s_add_u32 s14, s4, s1
	s_addc_u32 s15, s5, 0
	s_lshl_b32 s1, s6, 22
	s_load_dwordx2 s[4:5], s[8:9], 0x98
	s_add_u32 s18, s20, s1
	s_addc_u32 s19, s21, 0
	s_mul_i32 s1, s6, 0x1600000
	s_add_u32 s20, s22, s1
	s_addc_u32 s21, s23, 0
	s_mul_i32 s1, s6, 0xb00000
	s_waitcnt lgkmcnt(0)
	s_add_u32 s34, s4, s1
	s_movk_i32 s1, 0x2100
	v_mul_lo_u32 v0, v0, s1
	v_add_u32_e32 v2, s24, v0
	v_bfe_u32 v6, v1, 3, 3
	v_lshlrev_b32_e32 v5, 2, v3
	v_lshl_add_u32 v7, v3, 4, v2
	v_lshlrev_b32_e32 v0, 3, v3
	v_mul_u32_u24_e32 v3, 0x420, v3
	v_lshlrev_b32_e32 v12, 2, v6
	v_add3_u32 v12, v2, v3, v12
	v_mov_b32_e32 v2, 0xfffd7e00
	v_lshl_add_u32 v13, v4, 5, v2
	v_mov_b32_e32 v2, 0xffffd7e0
	s_addc_u32 s35, s5, 0
	v_mul_u32_u24_e32 v8, 0x84, v6
	v_or_b32_e32 v9, 8, v6
	v_or_b32_e32 v10, 16, v6
	v_or_b32_e32 v11, 24, v6
	s_lshl_b32 s12, s0, 8
	v_lshl_add_u32 v14, v4, 1, v2
	s_lshl_b32 s13, s0, 4
	s_mov_b64 s[38:39], 0
	s_branch .LBB0_405

.LBB0_421:
	s_or_b64 exec, exec, s[10:11]
	v_readlane_b32 s10, v253, 0
	s_mov_b32 s0, 0x80000
	s_mov_b32 s7, s54
	v_lshl_add_u32 v33, s10, 9, v1
	v_cmp_gt_i32_e32 vcc, s0, v33
	s_cmp_eq_u32 s6, 1
	s_cselect_b64 s[4:5], 0, -1
	s_and_b64 vcc, vcc, s[4:5]
	s_and_saveexec_b64 s[0:1], vcc
	s_cbranch_execz .LBB0_436
	s_load_dwordx2 s[4:5], s[8:9], 0xa8
	v_lshlrev_b32_e32 v0, 3, v1
	v_lshl_add_u32 v32, s10, 12, v0
	v_mov_b32_e32 v0, 0
	s_lshl_b32 s12, s7, 9
	s_lshl_b32 s66, s6, 23
	s_lshl_b32 s13, s7, 10
	s_lshl_b32 s14, s7, 13
	s_lshl_b32 s15, s7, 14
	s_mul_i32 s18, s7, 0x600
	s_mul_i32 s19, s7, 0x3000
	s_lshl_b32 s20, s7, 12
	s_mov_b64 s[6:7], 0
	v_mov_b32_e32 v1, v0
	v_mov_b32_e32 v2, v0
	v_mov_b32_e32 v3, v0
	v_mov_b32_e32 v4, v0
	v_mov_b32_e32 v5, v0
	v_mov_b32_e32 v6, v0
	v_mov_b32_e32 v7, v0
	v_mov_b32_e32 v12, v0
	v_mov_b32_e32 v13, v0
	v_mov_b32_e32 v14, v0
	v_mov_b32_e32 v15, v0
	v_mov_b32_e32 v8, v0
	v_mov_b32_e32 v9, v0
	v_mov_b32_e32 v10, v0
	v_mov_b32_e32 v11, v0
	v_mov_b32_e32 v16, v0
	v_mov_b32_e32 v17, v0
	v_mov_b32_e32 v18, v0
	v_mov_b32_e32 v19, v0
	v_mov_b32_e32 v20, v0
	v_mov_b32_e32 v21, v0
	v_mov_b32_e32 v22, v0
	v_mov_b32_e32 v23, v0
	s_branch .LBB0_424

.LBB0_653:
	s_waitcnt vmcnt(0)
	v_readlane_b32 s36, v254, 16
	v_readlane_b32 s37, v254, 17
	v_readlane_b32 s54, v254, 18
	s_mov_b32 s31, 0xd200000
	s_mov_b32 s72, 0xc2ce8ed0
	s_mov_b32 s73, 0x42b17218
	s_movk_i32 s61, 0x500
	s_mov_b64 s[56:57], 0xd200000
	s_mov_b32 s62, 0x3fb8aa3b
	v_readlane_b32 s63, v254, 26
	s_barrier
	v_readlane_b32 s55, v254, 19
	v_readlane_b32 s0, v254, 23
	s_cmp_lg_u32 s0, 7
	s_cbranch_scc1 .Lcv_done
	v_readlane_b32 s4, v253, 0
	s_cmpk_lt_i32 s4, 0x96
	s_cbranch_scc1 .Lcv_done
	s_sub_i32 s4, s4, 0x96
	v_lshrrev_b32_e32 v0, 6, v224
	v_and_b32_e32 v1, 63, v224
	v_readfirstlane_b32 s5, v0
	v_and_b32_e32 v2, 7, v1
	v_lshrrev_b32_e32 v3, 3, v1
	s_lshl_b32 s6, s4, 3
	s_add_i32 s6, s6, s5
	s_mul_i32 s7, s5, 0x2100
	s_add_i32 s7, s7, s67
	v_mul_u32_u24_e32 v4, 0x84, v3
	v_lshl_add_u32 v4, v2, 4, v4
	v_add_u32_e32 v4, s7, v4
	v_mul_u32_u24_e32 v5, 0x420, v2
	v_lshl_add_u32 v5, v3, 2, v5
	v_add_u32_e32 v5, s7, v5
	v_lshlrev_b32_e32 v88, 11, v3
	v_lshl_add_u32 v88, v2, 4, v88
	s_load_dwordx2 s[0:1], s[36:37], 0x48
	s_load_dwordx2 s[2:3], s[36:37], 0x78
	s_load_dwordx2 s[8:9], s[36:37], 0xa8
	s_waitcnt lgkmcnt(0)
	s_add_u32 s0, s0, 0xe08000
	s_addc_u32 s1, s1, 0
	s_add_u32 s2, s2, 0x400000
	s_addc_u32 s3, s3, 0
	s_cmpk_lt_i32 s6, 0x270
	s_cbranch_scc0 .Lcv_no2
	s_add_i32 s83, s6, 0x6a0
	s_cmpk_ge_i32 s83, 0x710
	s_cbranch_scc1 .Lcv_wout2
	s_mul_i32 s78, s83, 0x91
	s_lshr_b32 s78, s78, 14
	s_mul_i32 s79, s78, 0x71
	s_sub_i32 s79, s83, s79
	s_movk_i32 s80, 0xe08
	s_mov_b64 s[38:39], s[0:1]
	s_add_u32 s44, s8, 0x400000
	s_addc_u32 s45, s9, 0
	s_movk_i32 s81, 0xe04
	s_branch .Lcv_item2
.Lcv_wout2:
	s_sub_i32 s79, s83, 0x710
	s_lshr_b32 s78, s79, 5
	s_and_b32 s79, s79, 31
	s_movk_i32 s80, 0x400
	s_mov_b64 s[38:39], s[2:3]
	s_add_u32 s44, s8, 0xb80000
	s_addc_u32 s45, s9, 0
	s_mov_b32 s81, 0x7fffffff
.Lcv_item2:
	s_lshl_b32 s82, s79, 5
	v_lshl_add_u32 v6, v2, 2, s82
	v_min_i32_e32 v6, s81, v6
	v_mul_lo_u32 v7, v3, s80
	v_add_lshl_u32 v6, v7, v6, 2
	s_mul_i32 s82, s78, s80
	s_lshl_b32 s82, s82, 8
	s_add_u32 s38, s38, s82
	s_addc_u32 s39, s39, 0
	s_lshl_b32 s82, s80, 5
	global_load_dwordx4 v[148:151], v6, s[38:39] nt
	s_add_u32 s38, s38, s82
	s_addc_u32 s39, s39, 0
	global_load_dwordx4 v[152:155], v6, s[38:39] nt
	s_add_u32 s38, s38, s82
	s_addc_u32 s39, s39, 0
	global_load_dwordx4 v[156:159], v6, s[38:39] nt
	s_add_u32 s38, s38, s82
	s_addc_u32 s39, s39, 0
	global_load_dwordx4 v[160:163], v6, s[38:39] nt
	s_add_u32 s38, s38, s82
	s_addc_u32 s39, s39, 0
	global_load_dwordx4 v[164:167], v6, s[38:39] nt
	s_add_u32 s38, s38, s82
	s_addc_u32 s39, s39, 0
	global_load_dwordx4 v[168:171], v6, s[38:39] nt
	s_add_u32 s38, s38, s82
	s_addc_u32 s39, s39, 0
	global_load_dwordx4 v[172:175], v6, s[38:39] nt
	s_add_u32 s38, s38, s82
	s_addc_u32 s39, s39, 0
	global_load_dwordx4 v[176:179], v6, s[38:39] nt
	s_lshl_b32 s82, s79, 16
	s_add_u32 s44, s44, s82
	s_addc_u32 s45, s45, 0
	s_lshl_b32 s82, s78, 7
	s_add_u32 s44, s44, s82
	s_addc_u32 s45, s45, 0
.Lcv_no2:
	s_mov_b32 s83, s6
	s_cmpk_ge_i32 s83, 0x710
	s_cbranch_scc1 .Lcv_wout0
	s_mul_i32 s78, s83, 0x91
	s_lshr_b32 s78, s78, 14
	s_mul_i32 s79, s78, 0x71
	s_sub_i32 s79, s83, s79
	s_movk_i32 s80, 0xe08
	s_mov_b64 s[38:39], s[0:1]
	s_add_u32 s40, s8, 0x400000
	s_addc_u32 s41, s9, 0
	s_movk_i32 s81, 0xe04
	s_branch .Lcv_item0
.Lcv_wout0:
	s_sub_i32 s79, s83, 0x710
	s_lshr_b32 s78, s79, 5
	s_and_b32 s79, s79, 31
	s_movk_i32 s80, 0x400
	s_mov_b64 s[38:39], s[2:3]
	s_add_u32 s40, s8, 0xb80000
	s_addc_u32 s41, s9, 0
	s_mov_b32 s81, 0x7fffffff
.Lcv_item0:
	s_lshl_b32 s82, s79, 5
	v_lshl_add_u32 v6, v2, 2, s82
	v_min_i32_e32 v6, s81, v6
	v_mul_lo_u32 v7, v3, s80
	v_add_lshl_u32 v6, v7, v6, 2
	s_mul_i32 s82, s78, s80
	s_lshl_b32 s82, s82, 8
	s_add_u32 s38, s38, s82
	s_addc_u32 s39, s39, 0
	s_lshl_b32 s82, s80, 5
	global_load_dwordx4 v[8:11], v6, s[38:39] nt
	s_add_u32 s38, s38, s82
	s_addc_u32 s39, s39, 0
	global_load_dwordx4 v[12:15], v6, s[38:39] nt
	s_add_u32 s38, s38, s82
	s_addc_u32 s39, s39, 0
	global_load_dwordx4 v[16:19], v6, s[38:39] nt
	s_add_u32 s38, s38, s82
	s_addc_u32 s39, s39, 0
	global_load_dwordx4 v[20:23], v6, s[38:39] nt
	s_add_u32 s38, s38, s82
	s_addc_u32 s39, s39, 0
	global_load_dwordx4 v[24:27], v6, s[38:39] nt
	s_add_u32 s38, s38, s82
	s_addc_u32 s39, s39, 0
	global_load_dwordx4 v[28:31], v6, s[38:39] nt
	s_add_u32 s38, s38, s82
	s_addc_u32 s39, s39, 0
	global_load_dwordx4 v[32:35], v6, s[38:39] nt
	s_add_u32 s38, s38, s82
	s_addc_u32 s39, s39, 0
	global_load_dwordx4 v[36:39], v6, s[38:39] nt
	s_lshl_b32 s82, s79, 16
	s_add_u32 s40, s40, s82
	s_addc_u32 s41, s41, 0
	s_lshl_b32 s82, s78, 7
	s_add_u32 s40, s40, s82
	s_addc_u32 s41, s41, 0
	s_add_i32 s83, s6, 0x350
	s_cmpk_ge_i32 s83, 0x710
	s_cbranch_scc1 .Lcv_wout1
	s_mul_i32 s78, s83, 0x91
	s_lshr_b32 s78, s78, 14
	s_mul_i32 s79, s78, 0x71
	s_sub_i32 s79, s83, s79
	s_movk_i32 s80, 0xe08
	s_mov_b64 s[38:39], s[0:1]
	s_add_u32 s42, s8, 0x400000
	s_addc_u32 s43, s9, 0
	s_movk_i32 s81, 0xe04
	s_branch .Lcv_item1
.Lcv_wout1:
	s_sub_i32 s79, s83, 0x710
	s_lshr_b32 s78, s79, 5
	s_and_b32 s79, s79, 31
	s_movk_i32 s80, 0x400
	s_mov_b64 s[38:39], s[2:3]
	s_add_u32 s42, s8, 0xb80000
	s_addc_u32 s43, s9, 0
	s_mov_b32 s81, 0x7fffffff
.Lcv_item1:
	s_lshl_b32 s82, s79, 5
	v_lshl_add_u32 v6, v2, 2, s82
	v_min_i32_e32 v6, s81, v6
	v_mul_lo_u32 v7, v3, s80
	v_add_lshl_u32 v6, v7, v6, 2
	s_mul_i32 s82, s78, s80
	s_lshl_b32 s82, s82, 8
	s_add_u32 s38, s38, s82
	s_addc_u32 s39, s39, 0
	s_lshl_b32 s82, s80, 5
	global_load_dwordx4 v[116:119], v6, s[38:39] nt
	s_add_u32 s38, s38, s82
	s_addc_u32 s39, s39, 0
	global_load_dwordx4 v[120:123], v6, s[38:39] nt
	s_add_u32 s38, s38, s82
	s_addc_u32 s39, s39, 0
	global_load_dwordx4 v[124:127], v6, s[38:39] nt
	s_add_u32 s38, s38, s82
	s_addc_u32 s39, s39, 0
	global_load_dwordx4 v[128:131], v6, s[38:39] nt
	s_add_u32 s38, s38, s82
	s_addc_u32 s39, s39, 0
	global_load_dwordx4 v[132:135], v6, s[38:39] nt
	s_add_u32 s38, s38, s82
	s_addc_u32 s39, s39, 0
	global_load_dwordx4 v[136:139], v6, s[38:39] nt
	s_add_u32 s38, s38, s82
	s_addc_u32 s39, s39, 0
	global_load_dwordx4 v[140:143], v6, s[38:39] nt
	s_add_u32 s38, s38, s82
	s_addc_u32 s39, s39, 0
	global_load_dwordx4 v[144:147], v6, s[38:39] nt
	s_lshl_b32 s82, s79, 16
	s_add_u32 s42, s42, s82
	s_addc_u32 s43, s43, 0
	s_lshl_b32 s82, s78, 7
	s_add_u32 s42, s42, s82
	s_addc_u32 s43, s43, 0
	s_waitcnt vmcnt(15)
	ds_write2_b32 v4, v8, v9 offset1:1
	ds_write2_b32 v4, v10, v11 offset0:2 offset1:3
	s_waitcnt vmcnt(14)
	v_add_u32_e32 v7, 0x420, v4
	ds_write2_b32 v7, v12, v13 offset1:1
	ds_write2_b32 v7, v14, v15 offset0:2 offset1:3
	s_waitcnt vmcnt(13)
	v_add_u32_e32 v7, 0x840, v4
	ds_write2_b32 v7, v16, v17 offset1:1
	ds_write2_b32 v7, v18, v19 offset0:2 offset1:3
	s_waitcnt vmcnt(12)
	v_add_u32_e32 v7, 0xc60, v4
	ds_write2_b32 v7, v20, v21 offset1:1
	ds_write2_b32 v7, v22, v23 offset0:2 offset1:3
	s_waitcnt vmcnt(11)
	v_add_u32_e32 v7, 0x1080, v4
	ds_write2_b32 v7, v24, v25 offset1:1
	ds_write2_b32 v7, v26, v27 offset0:2 offset1:3
	s_waitcnt vmcnt(10)
	v_add_u32_e32 v7, 0x14a0, v4
	ds_write2_b32 v7, v28, v29 offset1:1
	ds_write2_b32 v7, v30, v31 offset0:2 offset1:3
	s_waitcnt vmcnt(9)
	v_add_u32_e32 v7, 0x18c0, v4
	ds_write2_b32 v7, v32, v33 offset1:1
	ds_write2_b32 v7, v34, v35 offset0:2 offset1:3
	s_waitcnt vmcnt(8)
	v_add_u32_e32 v7, 0x1ce0, v4
	ds_write2_b32 v7, v36, v37 offset1:1
	ds_write2_b32 v7, v38, v39 offset0:2 offset1:3
	s_waitcnt lgkmcnt(0)
	ds_read2_b32 v[40:41], v5 offset0:0 offset1:33
	ds_read2_b32 v[42:43], v5 offset0:66 offset1:99
	ds_read2_b32 v[44:45], v5 offset0:132 offset1:165
	ds_read2_b32 v[46:47], v5 offset0:198 offset1:231
	ds_read2_b32 v[48:49], v5 offset0:8 offset1:41
	ds_read2_b32 v[50:51], v5 offset0:74 offset1:107
	ds_read2_b32 v[52:53], v5 offset0:140 offset1:173
	ds_read2_b32 v[54:55], v5 offset0:206 offset1:239
	ds_read2_b32 v[56:57], v5 offset0:16 offset1:49
	ds_read2_b32 v[58:59], v5 offset0:82 offset1:115
	ds_read2_b32 v[60:61], v5 offset0:148 offset1:181
	ds_read2_b32 v[62:63], v5 offset0:214 offset1:247
	ds_read2_b32 v[64:65], v5 offset0:24 offset1:57
	ds_read2_b32 v[66:67], v5 offset0:90 offset1:123
	ds_read2_b32 v[68:69], v5 offset0:156 offset1:189
	ds_read2_b32 v[70:71], v5 offset0:222 offset1:255
	s_waitcnt lgkmcnt(12)
	v_cvt_pk_bf16_f32 v72, v40, v41
	v_cvt_pk_bf16_f32 v73, v42, v43
	v_cvt_pk_bf16_f32 v74, v44, v45
	v_cvt_pk_bf16_f32 v75, v46, v47
	global_store_dwordx4 v88, v[72:75], s[40:41]
	s_waitcnt lgkmcnt(8)
	v_cvt_pk_bf16_f32 v76, v48, v49
	v_cvt_pk_bf16_f32 v77, v50, v51
	v_cvt_pk_bf16_f32 v78, v52, v53
	v_cvt_pk_bf16_f32 v79, v54, v55
	s_add_u32 s40, s40, 0x4000
	s_addc_u32 s41, s41, 0
	global_store_dwordx4 v88, v[76:79], s[40:41]
	s_waitcnt lgkmcnt(4)
	v_cvt_pk_bf16_f32 v80, v56, v57
	v_cvt_pk_bf16_f32 v81, v58, v59
	v_cvt_pk_bf16_f32 v82, v60, v61
	v_cvt_pk_bf16_f32 v83, v62, v63
	s_add_u32 s40, s40, 0x4000
	s_addc_u32 s41, s41, 0
	global_store_dwordx4 v88, v[80:83], s[40:41]
	s_waitcnt lgkmcnt(0)
	v_cvt_pk_bf16_f32 v84, v64, v65
	v_cvt_pk_bf16_f32 v85, v66, v67
	v_cvt_pk_bf16_f32 v86, v68, v69
	v_cvt_pk_bf16_f32 v87, v70, v71
	s_add_u32 s40, s40, 0x4000
	s_addc_u32 s41, s41, 0
	global_store_dwordx4 v88, v[84:87], s[40:41]
	s_waitcnt vmcnt(7)
	ds_write2_b32 v4, v116, v117 offset1:1
	ds_write2_b32 v4, v118, v119 offset0:2 offset1:3
	s_waitcnt vmcnt(6)
	v_add_u32_e32 v7, 0x420, v4
	ds_write2_b32 v7, v120, v121 offset1:1
	ds_write2_b32 v7, v122, v123 offset0:2 offset1:3
	s_waitcnt vmcnt(5)
	v_add_u32_e32 v7, 0x840, v4
	ds_write2_b32 v7, v124, v125 offset1:1
	ds_write2_b32 v7, v126, v127 offset0:2 offset1:3
	s_waitcnt vmcnt(4)
	v_add_u32_e32 v7, 0xc60, v4
	ds_write2_b32 v7, v128, v129 offset1:1
	ds_write2_b32 v7, v130, v131 offset0:2 offset1:3
	s_waitcnt vmcnt(3)
	v_add_u32_e32 v7, 0x1080, v4
	ds_write2_b32 v7, v132, v133 offset1:1
	ds_write2_b32 v7, v134, v135 offset0:2 offset1:3
	s_waitcnt vmcnt(2)
	v_add_u32_e32 v7, 0x14a0, v4
	ds_write2_b32 v7, v136, v137 offset1:1
	ds_write2_b32 v7, v138, v139 offset0:2 offset1:3
	s_waitcnt vmcnt(1)
	v_add_u32_e32 v7, 0x18c0, v4
	ds_write2_b32 v7, v140, v141 offset1:1
	ds_write2_b32 v7, v142, v143 offset0:2 offset1:3
	s_waitcnt vmcnt(0)
	v_add_u32_e32 v7, 0x1ce0, v4
	ds_write2_b32 v7, v144, v145 offset1:1
	ds_write2_b32 v7, v146, v147 offset0:2 offset1:3
	s_waitcnt lgkmcnt(0)
	ds_read2_b32 v[40:41], v5 offset0:0 offset1:33
	ds_read2_b32 v[42:43], v5 offset0:66 offset1:99
	ds_read2_b32 v[44:45], v5 offset0:132 offset1:165
	ds_read2_b32 v[46:47], v5 offset0:198 offset1:231
	ds_read2_b32 v[48:49], v5 offset0:8 offset1:41
	ds_read2_b32 v[50:51], v5 offset0:74 offset1:107
	ds_read2_b32 v[52:53], v5 offset0:140 offset1:173
	ds_read2_b32 v[54:55], v5 offset0:206 offset1:239
	ds_read2_b32 v[56:57], v5 offset0:16 offset1:49
	ds_read2_b32 v[58:59], v5 offset0:82 offset1:115
	ds_read2_b32 v[60:61], v5 offset0:148 offset1:181
	ds_read2_b32 v[62:63], v5 offset0:214 offset1:247
	ds_read2_b32 v[64:65], v5 offset0:24 offset1:57
	ds_read2_b32 v[66:67], v5 offset0:90 offset1:123
	ds_read2_b32 v[68:69], v5 offset0:156 offset1:189
	ds_read2_b32 v[70:71], v5 offset0:222 offset1:255
	s_waitcnt lgkmcnt(12)
	v_cvt_pk_bf16_f32 v72, v40, v41
	v_cvt_pk_bf16_f32 v73, v42, v43
	v_cvt_pk_bf16_f32 v74, v44, v45
	v_cvt_pk_bf16_f32 v75, v46, v47
	global_store_dwordx4 v88, v[72:75], s[42:43]
	s_waitcnt lgkmcnt(8)
	v_cvt_pk_bf16_f32 v76, v48, v49
	v_cvt_pk_bf16_f32 v77, v50, v51
	v_cvt_pk_bf16_f32 v78, v52, v53
	v_cvt_pk_bf16_f32 v79, v54, v55
	s_add_u32 s42, s42, 0x4000
	s_addc_u32 s43, s43, 0
	global_store_dwordx4 v88, v[76:79], s[42:43]
	s_waitcnt lgkmcnt(4)
	v_cvt_pk_bf16_f32 v80, v56, v57
	v_cvt_pk_bf16_f32 v81, v58, v59
	v_cvt_pk_bf16_f32 v82, v60, v61
	v_cvt_pk_bf16_f32 v83, v62, v63
	s_add_u32 s42, s42, 0x4000
	s_addc_u32 s43, s43, 0
	global_store_dwordx4 v88, v[80:83], s[42:43]
	s_waitcnt lgkmcnt(0)
	v_cvt_pk_bf16_f32 v84, v64, v65
	v_cvt_pk_bf16_f32 v85, v66, v67
	v_cvt_pk_bf16_f32 v86, v68, v69
	v_cvt_pk_bf16_f32 v87, v70, v71
	s_add_u32 s42, s42, 0x4000
	s_addc_u32 s43, s43, 0
	global_store_dwordx4 v88, v[84:87], s[42:43]
	s_cmpk_lt_i32 s6, 0x270
	s_cbranch_scc0 .Lcv_caches
	s_waitcnt vmcnt(0)
	ds_write2_b32 v4, v148, v149 offset1:1
	ds_write2_b32 v4, v150, v151 offset0:2 offset1:3
	s_waitcnt vmcnt(0)
	v_add_u32_e32 v7, 0x420, v4
	ds_write2_b32 v7, v152, v153 offset1:1
	ds_write2_b32 v7, v154, v155 offset0:2 offset1:3
	s_waitcnt vmcnt(0)
	v_add_u32_e32 v7, 0x840, v4
	ds_write2_b32 v7, v156, v157 offset1:1
	ds_write2_b32 v7, v158, v159 offset0:2 offset1:3
	s_waitcnt vmcnt(0)
	v_add_u32_e32 v7, 0xc60, v4
	ds_write2_b32 v7, v160, v161 offset1:1
	ds_write2_b32 v7, v162, v163 offset0:2 offset1:3
	s_waitcnt vmcnt(0)
	v_add_u32_e32 v7, 0x1080, v4
	ds_write2_b32 v7, v164, v165 offset1:1
	ds_write2_b32 v7, v166, v167 offset0:2 offset1:3
	s_waitcnt vmcnt(0)
	v_add_u32_e32 v7, 0x14a0, v4
	ds_write2_b32 v7, v168, v169 offset1:1
	ds_write2_b32 v7, v170, v171 offset0:2 offset1:3
	s_waitcnt vmcnt(0)
	v_add_u32_e32 v7, 0x18c0, v4
	ds_write2_b32 v7, v172, v173 offset1:1
	ds_write2_b32 v7, v174, v175 offset0:2 offset1:3
	s_waitcnt vmcnt(0)
	v_add_u32_e32 v7, 0x1ce0, v4
	ds_write2_b32 v7, v176, v177 offset1:1
	ds_write2_b32 v7, v178, v179 offset0:2 offset1:3
	s_waitcnt lgkmcnt(0)
	ds_read2_b32 v[40:41], v5 offset0:0 offset1:33
	ds_read2_b32 v[42:43], v5 offset0:66 offset1:99
	ds_read2_b32 v[44:45], v5 offset0:132 offset1:165
	ds_read2_b32 v[46:47], v5 offset0:198 offset1:231
	ds_read2_b32 v[48:49], v5 offset0:8 offset1:41
	ds_read2_b32 v[50:51], v5 offset0:74 offset1:107
	ds_read2_b32 v[52:53], v5 offset0:140 offset1:173
	ds_read2_b32 v[54:55], v5 offset0:206 offset1:239
	ds_read2_b32 v[56:57], v5 offset0:16 offset1:49
	ds_read2_b32 v[58:59], v5 offset0:82 offset1:115
	ds_read2_b32 v[60:61], v5 offset0:148 offset1:181
	ds_read2_b32 v[62:63], v5 offset0:214 offset1:247
	ds_read2_b32 v[64:65], v5 offset0:24 offset1:57
	ds_read2_b32 v[66:67], v5 offset0:90 offset1:123
	ds_read2_b32 v[68:69], v5 offset0:156 offset1:189
	ds_read2_b32 v[70:71], v5 offset0:222 offset1:255
	s_waitcnt lgkmcnt(12)
	v_cvt_pk_bf16_f32 v72, v40, v41
	v_cvt_pk_bf16_f32 v73, v42, v43
	v_cvt_pk_bf16_f32 v74, v44, v45
	v_cvt_pk_bf16_f32 v75, v46, v47
	global_store_dwordx4 v88, v[72:75], s[44:45]
	s_waitcnt lgkmcnt(8)
	v_cvt_pk_bf16_f32 v76, v48, v49
	v_cvt_pk_bf16_f32 v77, v50, v51
	v_cvt_pk_bf16_f32 v78, v52, v53
	v_cvt_pk_bf16_f32 v79, v54, v55
	s_add_u32 s44, s44, 0x4000
	s_addc_u32 s45, s45, 0
	global_store_dwordx4 v88, v[76:79], s[44:45]
	s_waitcnt lgkmcnt(4)
	v_cvt_pk_bf16_f32 v80, v56, v57
	v_cvt_pk_bf16_f32 v81, v58, v59
	v_cvt_pk_bf16_f32 v82, v60, v61
	v_cvt_pk_bf16_f32 v83, v62, v63
	s_add_u32 s44, s44, 0x4000
	s_addc_u32 s45, s45, 0
	global_store_dwordx4 v88, v[80:83], s[44:45]
	s_waitcnt lgkmcnt(0)
	v_cvt_pk_bf16_f32 v84, v64, v65
	v_cvt_pk_bf16_f32 v85, v66, v67
	v_cvt_pk_bf16_f32 v86, v68, v69
	v_cvt_pk_bf16_f32 v87, v70, v71
	s_add_u32 s44, s44, 0x4000
	s_addc_u32 s45, s45, 0
	global_store_dwordx4 v88, v[84:87], s[44:45]
.Lcv_caches:
	s_load_dwordx4 s[0:3], s[36:37], 0x10
	s_waitcnt lgkmcnt(0)
	s_add_u32 s0, s0, 0x800000
	s_addc_u32 s1, s1, 0
	s_add_u32 s2, s2, 0x800000
	s_addc_u32 s3, s3, 0
	s_add_u32 s38, s8, 0xf400000
	s_addc_u32 s39, s9, 0
	s_add_u32 s40, s8, 0xf800000
	s_addc_u32 s41, s9, 0
	v_lshl_add_u32 v0, s4, 9, v224
	s_lshl_b32 s42, s4, 9
	s_lshl_b32 s43, s5, 6
	s_add_i32 s42, s42, s43
	s_cmp_lt_u32 s42, 0xb000
	s_cbranch_scc0 .Lcv_noc4
	v_add_u32_e32 v1, 0x35000, v0
	v_lshlrev_b32_e32 v1, 5, v1
	global_load_dwordx4 v[116:119], v1, s[0:1] nt
	global_load_dwordx4 v[120:123], v1, s[0:1] offset:16 nt
	global_load_dwordx4 v[124:127], v1, s[2:3] nt
	global_load_dwordx4 v[128:131], v1, s[2:3] offset:16 nt
.Lcv_noc4:
	v_mov_b32_e32 v1, v0
	v_lshlrev_b32_e32 v1, 5, v1
	global_load_dwordx4 v[8:11], v1, s[0:1] nt
	global_load_dwordx4 v[12:15], v1, s[0:1] offset:16 nt
	global_load_dwordx4 v[16:19], v1, s[2:3] nt
	global_load_dwordx4 v[20:23], v1, s[2:3] offset:16 nt
	v_add_u32_e32 v1, 0xd400, v0
	v_lshlrev_b32_e32 v1, 5, v1
	global_load_dwordx4 v[24:27], v1, s[0:1] nt
	global_load_dwordx4 v[28:31], v1, s[0:1] offset:16 nt
	global_load_dwordx4 v[32:35], v1, s[2:3] nt
	global_load_dwordx4 v[36:39], v1, s[2:3] offset:16 nt
	v_add_u32_e32 v1, 0x1a800, v0
	v_lshlrev_b32_e32 v1, 5, v1
	global_load_dwordx4 v[40:43], v1, s[0:1] nt
	global_load_dwordx4 v[44:47], v1, s[0:1] offset:16 nt
	global_load_dwordx4 v[48:51], v1, s[2:3] nt
	global_load_dwordx4 v[52:55], v1, s[2:3] offset:16 nt
	v_add_u32_e32 v1, 0x27c00, v0
	v_lshlrev_b32_e32 v1, 5, v1
	global_load_dwordx4 v[56:59], v1, s[0:1] nt
	global_load_dwordx4 v[60:63], v1, s[0:1] offset:16 nt
	global_load_dwordx4 v[64:67], v1, s[2:3] nt
	global_load_dwordx4 v[68:71], v1, s[2:3] offset:16 nt
	s_waitcnt vmcnt(0)
	v_mov_b32_e32 v2, v0
	v_lshlrev_b32_e32 v2, 4, v2
	v_cvt_pk_bf16_f32 v72, v8, v9
	v_cvt_pk_bf16_f32 v73, v10, v11
	v_cvt_pk_bf16_f32 v74, v12, v13
	v_cvt_pk_bf16_f32 v75, v14, v15
	global_store_dwordx4 v2, v[72:75], s[38:39]
	v_cvt_pk_bf16_f32 v76, v16, v17
	v_cvt_pk_bf16_f32 v77, v18, v19
	v_cvt_pk_bf16_f32 v78, v20, v21
	v_cvt_pk_bf16_f32 v79, v22, v23
	global_store_dwordx4 v2, v[76:79], s[40:41]
	v_add_u32_e32 v2, 0xd400, v0
	v_lshlrev_b32_e32 v2, 4, v2
	v_cvt_pk_bf16_f32 v72, v24, v25
	v_cvt_pk_bf16_f32 v73, v26, v27
	v_cvt_pk_bf16_f32 v74, v28, v29
	v_cvt_pk_bf16_f32 v75, v30, v31
	global_store_dwordx4 v2, v[72:75], s[38:39]
	v_cvt_pk_bf16_f32 v76, v32, v33
	v_cvt_pk_bf16_f32 v77, v34, v35
	v_cvt_pk_bf16_f32 v78, v36, v37
	v_cvt_pk_bf16_f32 v79, v38, v39
	global_store_dwordx4 v2, v[76:79], s[40:41]
	v_add_u32_e32 v2, 0x1a800, v0
	v_lshlrev_b32_e32 v2, 4, v2
	v_cvt_pk_bf16_f32 v72, v40, v41
	v_cvt_pk_bf16_f32 v73, v42, v43
	v_cvt_pk_bf16_f32 v74, v44, v45
	v_cvt_pk_bf16_f32 v75, v46, v47
	global_store_dwordx4 v2, v[72:75], s[38:39]
	v_cvt_pk_bf16_f32 v76, v48, v49
	v_cvt_pk_bf16_f32 v77, v50, v51
	v_cvt_pk_bf16_f32 v78, v52, v53
	v_cvt_pk_bf16_f32 v79, v54, v55
	global_store_dwordx4 v2, v[76:79], s[40:41]
	v_add_u32_e32 v2, 0x27c00, v0
	v_lshlrev_b32_e32 v2, 4, v2
	v_cvt_pk_bf16_f32 v72, v56, v57
	v_cvt_pk_bf16_f32 v73, v58, v59
	v_cvt_pk_bf16_f32 v74, v60, v61
	v_cvt_pk_bf16_f32 v75, v62, v63
	global_store_dwordx4 v2, v[72:75], s[38:39]
	v_cvt_pk_bf16_f32 v76, v64, v65
	v_cvt_pk_bf16_f32 v77, v66, v67
	v_cvt_pk_bf16_f32 v78, v68, v69
	v_cvt_pk_bf16_f32 v79, v70, v71
	global_store_dwordx4 v2, v[76:79], s[40:41]
	s_cmp_lt_u32 s42, 0xb000
	s_cbranch_scc0 .Lcv_done
	v_add_u32_e32 v2, 0x35000, v0
	v_lshlrev_b32_e32 v2, 4, v2
	v_cvt_pk_bf16_f32 v72, v116, v117
	v_cvt_pk_bf16_f32 v73, v118, v119
	v_cvt_pk_bf16_f32 v74, v120, v121
	v_cvt_pk_bf16_f32 v75, v122, v123
	global_store_dwordx4 v2, v[72:75], s[38:39]
	v_cvt_pk_bf16_f32 v76, v124, v125
	v_cvt_pk_bf16_f32 v77, v126, v127
	v_cvt_pk_bf16_f32 v78, v128, v129
	v_cvt_pk_bf16_f32 v79, v130, v131
	global_store_dwordx4 v2, v[76:79], s[40:41]
.Lcv_done:
.LBB0_654:
	s_cmp_lt_i32 s63, 9
	s_cbranch_scc1 .LBB0_656
	s_cmp_eq_u32 s63, 9
	s_cselect_b64 s[0:1], -1, 0
	s_cbranch_execz .LBB0_657
	s_branch .LBB0_658
